# P7: prefetched next-unit loads waited before the second workgroup barrier (before the list stores are issued) instead of counted waits after them
# baseline (speedup 1.0000x reference)
.LBB0_852:
	s_and_b64 vcc, exec, s[0:1]
	s_cbranch_vccnz .LBB0_882
	v_mov_b32_e32 v87, 0
	v_lshlrev_b32_e32 v86, 2, v198
	v_or_b32_e32 v93, s8, v198
	v_lshl_add_u64 v[4:5], s[38:39], 0, v[86:87]
	s_mov_b64 s[8:9], 0x10000
	v_or_b32_e32 v9, 0x200, v0
	v_lshrrev_b32_e32 v6, 5, v198
	v_lshl_add_u64 v[88:89], v[4:5], 0, s[8:9]
	v_lshrrev_b32_e32 v104, 4, v0
	v_lshlrev_b32_e32 v5, 4, v0
	v_lshrrev_b32_e32 v105, 4, v9
	v_lshlrev_b32_e32 v92, 2, v6
	v_lshlrev_b32_e32 v4, 8, v104
	v_and_b32_e32 v7, 0xf0, v5
	s_movk_i32 s8, 0x70
	v_and_b32_e32 v8, 0x70, v0
	v_lshlrev_b32_e32 v9, 8, v105
	v_lshlrev_b32_e32 v6, 4, v6
	v_bitop3_b32 v4, v7, v4, v8 bitop3:0xde
	v_bitop3_b32 v7, v9, v7, v8 bitop3:0xf6
	v_and_b32_e32 v8, 0x70, v5
	v_bitop3_b32 v5, v6, v5, s8 bitop3:0x78
	s_movk_i32 s8, 0x60
	s_add_u32 s51, s38, 0x2200000
	v_bitop3_b32 v11, v6, v8, s8 bitop3:0x36
	s_movk_i32 s8, 0x80
	s_addc_u32 s52, s39, 0
	v_bitop3_b32 v12, v6, v8, s8 bitop3:0x36
	s_movk_i32 s8, 0xa0
	s_add_u32 s53, s38, 0x2000000
	v_bitop3_b32 v13, v6, v8, s8 bitop3:0x36
	s_movk_i32 s8, 0xc0
	s_addc_u32 s54, s39, 0
	v_bitop3_b32 v14, v6, v8, s8 bitop3:0x36
	s_movk_i32 s8, 0xe0
	v_lshl_add_u32 v3, v3, 8, 0
	v_bitop3_b32 v9, v6, v8, 32 bitop3:0x36
	v_bitop3_b32 v10, v6, v8, 64 bitop3:0x36
	v_bitop3_b32 v6, v6, v8, s8 bitop3:0x36
	s_cmp_lt_u32 s31, 64
	v_add_u32_e32 v114, 0, v86
	v_lshlrev_b32_e32 v86, 2, v2
	v_mbcnt_lo_u32_b32 v2, -1, 0
	s_mov_b32 s23, 0
	v_lshl_add_u32 v94, v0, 2, 0
	v_or_b32_e32 v95, 2, v92
	v_or_b32_e32 v96, 8, v92
	v_or_b32_e32 v97, 10, v92
	v_or_b32_e32 v98, 16, v92
	v_or_b32_e32 v99, 18, v92
	v_or_b32_e32 v100, 24, v92
	v_or_b32_e32 v101, 26, v92
	v_cmp_gt_u32_e64 s[0:1], 32, v198
	v_cmp_gt_u32_e64 s[4:5], 2, v198
	v_cmp_gt_u32_e64 s[6:7], 8, v198
	v_or_b32_e32 v102, 0x100, v93
	v_or_b32_e32 v103, 0x200, v93
	v_or_b32_e32 v106, 1, v92
	v_or_b32_e32 v107, 3, v92
	v_or_b32_e32 v108, 9, v92
	v_or_b32_e32 v109, 11, v92
	v_or_b32_e32 v110, 17, v92
	v_or_b32_e32 v111, 19, v92
	v_or_b32_e32 v112, 25, v92
	v_or_b32_e32 v113, 27, v92
	s_cselect_b64 s[24:25], -1, 0
	v_cmp_eq_u32_e64 s[8:9], 0, v198
	v_cmp_ne_u32_e64 s[10:11], 0, v198
	v_cmp_gt_u32_e64 s[12:13], 4, v198
	v_cmp_gt_u32_e64 s[14:15], 16, v198
	v_lshl_add_u64 v[90:91], s[18:19], 0, v[86:87]
	s_movk_i32 s55, 0x7fff
	v_add_u32_e32 v115, 0, v4
	v_add_u32_e32 v116, 0, v7
	v_add_u32_e32 v117, v3, v5
	v_add_u32_e32 v118, v3, v9
	v_add_u32_e32 v119, v3, v10
	v_add_u32_e32 v120, v3, v11
	v_add_u32_e32 v121, v3, v12
	v_add_u32_e32 v122, v3, v13
	v_add_u32_e32 v123, v3, v14
	v_add_u32_e32 v124, v3, v6
	s_mov_b64 s[26:27], 0x4000
	s_movk_i32 s56, 0x4000
	s_movk_i32 s57, 0xffc0
	v_mov_b32_e32 v125, 1
	v_mbcnt_hi_u32_b32 v126, -1, v2
	s_mov_b32 s58, s50
	s_waitcnt vmcnt(0)
	s_branch .LBB0_855

.LBB0_855:
	s_add_i32 s58, s58, s30
	s_cmpk_lt_i32 s58, 0x400
	s_cselect_b64 s[18:19], -1, 0
	s_cmpk_gt_i32 s58, 0x3ff
	s_cselect_b64 s[28:29], -1, 0
	s_and_b32 s22, s58, 63
	s_cmp_eq_u32 s22, 0
	s_cselect_b64 s[46:47], -1, 0
	s_and_b64 s[46:47], s[18:19], s[46:47]
	s_and_b64 vcc, exec, s[46:47]
	s_cbranch_vccnz .LBB0_855
	s_and_b32 s59, s50, 63
	v_cmp_gt_u32_e32 vcc, s59, v104
	s_nop 0
	v_cndmask_b32_e32 v2, 0, v38, vcc
	v_bfe_u32 v3, v2, 16, 1
	v_add3_u32 v3, v2, v3, s55
	v_and_b32_e32 v4, 0xffff0000, v3
	v_sub_f32_e32 v6, v2, v4
	v_cndmask_b32_e32 v2, 0, v39, vcc
	v_bfe_u32 v4, v2, 16, 1
	v_add3_u32 v4, v2, v4, s55
	v_and_b32_e32 v4, 0xffff0000, v4
	v_sub_f32_e32 v7, v2, v4
	v_cndmask_b32_e32 v2, 0, v40, vcc
	v_bfe_u32 v5, v2, 16, 1
	v_add3_u32 v5, v2, v5, s55
	v_and_b32_e32 v8, 0xffff0000, v5
	v_sub_f32_e32 v8, v2, v8
	v_cndmask_b32_e32 v2, 0, v41, vcc
	v_bfe_u32 v9, v2, 16, 1
	v_add3_u32 v9, v2, v9, s55
	v_and_b32_e32 v9, 0xffff0000, v9
	v_sub_f32_e32 v10, v2, v9
	v_cndmask_b32_e32 v2, 0, v58, vcc
	v_bfe_u32 v11, v2, 16, 1
	v_add3_u32 v11, v2, v11, s55
	v_and_b32_e32 v12, 0xffff0000, v11
	v_sub_f32_e32 v12, v2, v12
	v_cndmask_b32_e32 v2, 0, v59, vcc
	v_bfe_u32 v13, v2, 16, 1
	v_add3_u32 v13, v2, v13, s55
	v_and_b32_e32 v13, 0xffff0000, v13
	v_sub_f32_e32 v14, v2, v13
	v_cndmask_b32_e32 v2, 0, v60, vcc
	v_bfe_u32 v15, v2, 16, 1
	v_add3_u32 v15, v2, v15, s55
	v_and_b32_e32 v16, 0xffff0000, v15
	v_sub_f32_e32 v16, v2, v16
	v_cndmask_b32_e32 v2, 0, v61, vcc
	v_bfe_u32 v17, v2, 16, 1
	v_add3_u32 v17, v2, v17, s55
	v_and_b32_e32 v17, 0xffff0000, v17
	v_sub_f32_e32 v18, v2, v17
	v_or_b32_sdwa v2, v4, v3 dst_sel:DWORD dst_unused:UNUSED_PAD src0_sel:DWORD src1_sel:WORD_1
	v_or_b32_sdwa v3, v9, v5 dst_sel:DWORD dst_unused:UNUSED_PAD src0_sel:DWORD src1_sel:WORD_1
	v_or_b32_sdwa v4, v13, v11 dst_sel:DWORD dst_unused:UNUSED_PAD src0_sel:DWORD src1_sel:WORD_1
	v_or_b32_sdwa v5, v17, v15 dst_sel:DWORD dst_unused:UNUSED_PAD src0_sel:DWORD src1_sel:WORD_1
	v_cmp_gt_u32_e32 vcc, s59, v105
	v_cvt_pk_bf16_f32 v6, v6, v7
	v_cvt_pk_bf16_f32 v7, v8, v10
	v_cvt_pk_bf16_f32 v8, v12, v14
	v_cvt_pk_bf16_f32 v9, v16, v18
	ds_write_b128 v115, v[2:5]
	ds_write_b128 v115, v[6:9] offset:16384
	v_cndmask_b32_e32 v2, 0, v74, vcc
	v_bfe_u32 v3, v2, 16, 1
	v_add3_u32 v3, v2, v3, s55
	v_and_b32_e32 v4, 0xffff0000, v3
	v_sub_f32_e32 v6, v2, v4
	v_cndmask_b32_e32 v2, 0, v75, vcc
	v_bfe_u32 v4, v2, 16, 1
	v_add3_u32 v4, v2, v4, s55
	v_and_b32_e32 v4, 0xffff0000, v4
	v_sub_f32_e32 v7, v2, v4
	v_cndmask_b32_e32 v2, 0, v76, vcc
	v_bfe_u32 v5, v2, 16, 1
	v_add3_u32 v5, v2, v5, s55
	v_and_b32_e32 v8, 0xffff0000, v5
	v_sub_f32_e32 v8, v2, v8
	v_cndmask_b32_e32 v2, 0, v77, vcc
	v_bfe_u32 v9, v2, 16, 1
	v_add3_u32 v9, v2, v9, s55
	v_and_b32_e32 v9, 0xffff0000, v9
	v_sub_f32_e32 v10, v2, v9
	v_cndmask_b32_e32 v2, 0, v78, vcc
	v_bfe_u32 v11, v2, 16, 1
	v_add3_u32 v11, v2, v11, s55
	v_and_b32_e32 v12, 0xffff0000, v11
	v_sub_f32_e32 v12, v2, v12
	v_cndmask_b32_e32 v2, 0, v79, vcc
	v_bfe_u32 v13, v2, 16, 1
	v_add3_u32 v13, v2, v13, s55
	v_and_b32_e32 v13, 0xffff0000, v13
	v_sub_f32_e32 v14, v2, v13
	v_cndmask_b32_e32 v2, 0, v80, vcc
	v_bfe_u32 v15, v2, 16, 1
	v_add3_u32 v15, v2, v15, s55
	v_and_b32_e32 v16, 0xffff0000, v15
	v_sub_f32_e32 v16, v2, v16
	v_cndmask_b32_e32 v2, 0, v81, vcc
	v_bfe_u32 v17, v2, 16, 1
	v_add3_u32 v17, v2, v17, s55
	v_and_b32_e32 v17, 0xffff0000, v17
	v_sub_f32_e32 v18, v2, v17
	v_or_b32_sdwa v2, v4, v3 dst_sel:DWORD dst_unused:UNUSED_PAD src0_sel:DWORD src1_sel:WORD_1
	v_or_b32_sdwa v3, v9, v5 dst_sel:DWORD dst_unused:UNUSED_PAD src0_sel:DWORD src1_sel:WORD_1
	v_or_b32_sdwa v4, v13, v11 dst_sel:DWORD dst_unused:UNUSED_PAD src0_sel:DWORD src1_sel:WORD_1
	v_or_b32_sdwa v5, v17, v15 dst_sel:DWORD dst_unused:UNUSED_PAD src0_sel:DWORD src1_sel:WORD_1
	v_cvt_pk_bf16_f32 v6, v6, v7
	v_cvt_pk_bf16_f32 v7, v8, v10
	v_cvt_pk_bf16_f32 v8, v12, v14
	v_cvt_pk_bf16_f32 v9, v16, v18
	ds_write_b128 v116, v[2:5]
	ds_write_b128 v116, v[6:9] offset:16384
	s_and_saveexec_b64 s[46:47], s[16:17]
	ds_write_b32 v94, v87 offset:32768
	s_or_b64 exec, exec, s[46:47]
	s_waitcnt lgkmcnt(0)
	s_barrier
	ds_read_b128 v[136:139], v117
	ds_read_b128 v[140:143], v117 offset:8192
	ds_read_b128 v[144:147], v118
	ds_read_b128 v[148:151], v118 offset:8192
	ds_read_b128 v[152:155], v119
	ds_read_b128 v[156:159], v119 offset:8192
	ds_read_b128 v[160:163], v120
	ds_read_b128 v[164:167], v120 offset:8192
	s_waitcnt lgkmcnt(7)
	v_mfma_f32_32x32x16_bf16 v[18:33], v[136:139], v[34:37], 0
	s_andn2_b64 vcc, exec, s[18:19]
	s_waitcnt lgkmcnt(6)
	v_mfma_f32_32x32x16_bf16 v[2:17], v[140:143], v[34:37], 0
	ds_read_b128 v[136:139], v121
	s_waitcnt lgkmcnt(6)
	v_mfma_f32_32x32x16_bf16 v[18:33], v[144:147], v[42:45], v[18:33]
	ds_read_b128 v[140:143], v121 offset:8192
	s_waitcnt lgkmcnt(6)
	v_mfma_f32_32x32x16_bf16 v[2:17], v[148:151], v[42:45], v[2:17]
	ds_read_b128 v[144:147], v122
	s_waitcnt lgkmcnt(6)
	v_mfma_f32_32x32x16_bf16 v[18:33], v[152:155], v[46:49], v[18:33]
	ds_read_b128 v[148:151], v122 offset:8192
	s_waitcnt lgkmcnt(6)
	v_mfma_f32_32x32x16_bf16 v[2:17], v[156:159], v[46:49], v[2:17]
	ds_read_b128 v[152:155], v123
	s_waitcnt lgkmcnt(6)
	v_mfma_f32_32x32x16_bf16 v[18:33], v[160:163], v[50:53], v[18:33]
	ds_read_b128 v[156:159], v123 offset:8192
	s_waitcnt lgkmcnt(6)
	v_mfma_f32_32x32x16_bf16 v[2:17], v[164:167], v[50:53], v[2:17]
	ds_read_b128 v[160:163], v124
	s_waitcnt lgkmcnt(6)
	v_mfma_f32_32x32x16_bf16 v[18:33], v[136:139], v[54:57], v[18:33]
	ds_read_b128 v[164:167], v124 offset:8192
	s_waitcnt lgkmcnt(6)
	v_mfma_f32_32x32x16_bf16 v[2:17], v[140:143], v[54:57], v[2:17]
	ds_read_b128 v[136:139], v117 offset:16384
	s_waitcnt lgkmcnt(6)
	v_mfma_f32_32x32x16_bf16 v[18:33], v[144:147], v[62:65], v[18:33]
	ds_read_b128 v[140:143], v117 offset:24576
	s_waitcnt lgkmcnt(6)
	v_mfma_f32_32x32x16_bf16 v[2:17], v[148:151], v[62:65], v[2:17]
	ds_read_b128 v[144:147], v118 offset:16384
	s_waitcnt lgkmcnt(6)
	v_mfma_f32_32x32x16_bf16 v[18:33], v[152:155], v[66:69], v[18:33]
	ds_read_b128 v[148:151], v118 offset:24576
	s_waitcnt lgkmcnt(6)
	v_mfma_f32_32x32x16_bf16 v[2:17], v[156:159], v[66:69], v[2:17]
	ds_read_b128 v[152:155], v119 offset:16384
	s_waitcnt lgkmcnt(6)
	v_mfma_f32_32x32x16_bf16 v[18:33], v[160:163], v[70:73], v[18:33]
	ds_read_b128 v[156:159], v119 offset:24576
	s_waitcnt lgkmcnt(6)
	v_mfma_f32_32x32x16_bf16 v[2:17], v[164:167], v[70:73], v[2:17]
	ds_read_b128 v[160:163], v120 offset:16384
	s_waitcnt lgkmcnt(6)
	v_mfma_f32_32x32x16_bf16 v[18:33], v[136:139], v[34:37], v[18:33]
	ds_read_b128 v[164:167], v120 offset:24576
	s_waitcnt lgkmcnt(6)
	v_mfma_f32_32x32x16_bf16 v[2:17], v[140:143], v[34:37], v[2:17]
	ds_read_b128 v[136:139], v121 offset:16384
	s_waitcnt lgkmcnt(6)
	v_mfma_f32_32x32x16_bf16 v[18:33], v[144:147], v[42:45], v[18:33]
	ds_read_b128 v[140:143], v121 offset:24576
	s_waitcnt lgkmcnt(6)
	v_mfma_f32_32x32x16_bf16 v[2:17], v[148:151], v[42:45], v[2:17]
	ds_read_b128 v[144:147], v122 offset:16384
	s_waitcnt lgkmcnt(6)
	v_mfma_f32_32x32x16_bf16 v[18:33], v[152:155], v[46:49], v[18:33]
	ds_read_b128 v[148:151], v122 offset:24576
	s_waitcnt lgkmcnt(6)
	v_mfma_f32_32x32x16_bf16 v[2:17], v[156:159], v[46:49], v[2:17]
	ds_read_b128 v[152:155], v123 offset:16384
	s_waitcnt lgkmcnt(6)
	v_mfma_f32_32x32x16_bf16 v[18:33], v[160:163], v[50:53], v[18:33]
	ds_read_b128 v[156:159], v123 offset:24576
	s_waitcnt lgkmcnt(6)
	v_mfma_f32_32x32x16_bf16 v[2:17], v[164:167], v[50:53], v[2:17]
	ds_read_b128 v[160:163], v124 offset:16384
	s_waitcnt lgkmcnt(6)
	v_mfma_f32_32x32x16_bf16 v[18:33], v[136:139], v[54:57], v[18:33]
	ds_read_b128 v[164:167], v124 offset:24576
	s_waitcnt lgkmcnt(6)
	v_mfma_f32_32x32x16_bf16 v[2:17], v[140:143], v[54:57], v[2:17]
	s_waitcnt lgkmcnt(5)
	v_mfma_f32_32x32x16_bf16 v[18:33], v[144:147], v[62:65], v[18:33]
	s_waitcnt lgkmcnt(4)
	v_mfma_f32_32x32x16_bf16 v[2:17], v[148:151], v[62:65], v[2:17]
	s_waitcnt lgkmcnt(3)
	v_mfma_f32_32x32x16_bf16 v[18:33], v[152:155], v[66:69], v[18:33]
	s_waitcnt lgkmcnt(2)
	v_mfma_f32_32x32x16_bf16 v[2:17], v[156:159], v[66:69], v[2:17]
	s_waitcnt lgkmcnt(1)
	v_mfma_f32_32x32x16_bf16 v[18:33], v[160:163], v[70:73], v[18:33]
	s_waitcnt lgkmcnt(0)
	v_mfma_f32_32x32x16_bf16 v[2:17], v[164:167], v[70:73], v[2:17]
	s_cbranch_vccnz .LBB0_860
	s_ashr_i32 s18, s58, 9
	s_bfe_u32 s60, s58, 0x30006
	s_lshl_b32 s19, s18, 3
	s_or_b32 s46, s19, s60
	s_ashr_i32 s47, s46, 31
	s_ashr_i32 s19, s18, 31
	s_lshl_b64 s[46:47], s[46:47], 15
	s_lshl_b64 s[18:19], s[18:19], 25
	v_lshl_add_u32 v86, s22, 8, v1
	s_add_u32 s18, s48, s18
	v_lshlrev_b64 v[34:35], 11, v[86:87]
	s_addc_u32 s19, s49, s19
	v_lshl_add_u64 v[34:35], s[18:19], 0, v[34:35]
	s_lshl_b32 s22, s60, 8
	v_lshl_add_u64 v[34:35], v[34:35], 0, s[22:23]
	v_mov_b32_e32 v83, v87
	v_lshl_add_u64 v[38:39], v[34:35], 0, v[82:83]
	global_load_dwordx4 v[34:37], v[38:39], off
	global_load_dwordx4 v[42:45], v[38:39], off offset:32
	global_load_dwordx4 v[46:49], v[38:39], off offset:64
	global_load_dwordx4 v[50:53], v[38:39], off offset:96
	global_load_dwordx4 v[54:57], v[38:39], off offset:128
	global_load_dwordx4 v[62:65], v[38:39], off offset:160
	global_load_dwordx4 v[66:69], v[38:39], off offset:192
	global_load_dwordx4 v[70:73], v[38:39], off offset:224
	v_lshl_add_u64 v[38:39], v[90:91], 0, s[46:47]
	v_mov_b32_e32 v85, v87
	v_lshl_add_u64 v[74:75], v[38:39], 0, v[84:85]
	global_load_dwordx4 v[38:41], v[74:75], off
	global_load_dwordx4 v[58:61], v[74:75], off offset:16
	v_lshl_add_u64 v[78:79], v[74:75], 0, s[26:27]
	v_add_co_u32_e32 v74, vcc, s56, v74
	s_nop 1
	v_addc_co_u32_e32 v75, vcc, 0, v75, vcc
	global_load_dwordx4 v[74:77], v[74:75], off
	s_nop 0
	global_load_dwordx4 v[78:81], v[78:79], off offset:16

.LBB0_866:
	s_or_b64 exec, exec, s[18:19]
	s_andn2_b64 vcc, exec, s[24:25]
	s_waitcnt vmcnt(0) lgkmcnt(0)
	s_barrier
	s_cbranch_vccnz .LBB0_874
	ds_read_b32 v9, v114 offset:32768
	v_add_u32_e32 v10, -1, v126
	v_cmp_lt_i32_e32 vcc, v10, v8
	v_add_u32_e32 v11, -2, v126
	v_add_u32_e32 v12, -4, v126
	v_cndmask_b32_e32 v10, v10, v126, vcc
	v_lshlrev_b32_e32 v10, 2, v10
	s_waitcnt lgkmcnt(0)
	ds_bpermute_b32 v10, v10, v9
	v_cmp_lt_i32_e32 vcc, v11, v8
	s_mul_i32 s18, s50, 0x90
	s_mul_hi_i32 s19, s50, 0x90
	v_cndmask_b32_e32 v11, v11, v126, vcc
	s_waitcnt lgkmcnt(0)
	v_cndmask_b32_e64 v10, v10, 0, s[8:9]
	v_lshlrev_b32_e32 v11, 2, v11
	v_add_u32_e32 v10, v10, v9
	ds_bpermute_b32 v11, v11, v10
	v_cmp_lt_i32_e32 vcc, v12, v8
	s_add_u32 s18, s51, s18
	s_addc_u32 s19, s52, s19
	v_cndmask_b32_e32 v12, v12, v126, vcc
	s_waitcnt lgkmcnt(0)
	v_cndmask_b32_e64 v11, v11, 0, s[4:5]
	v_lshlrev_b32_e32 v12, 2, v12
	v_add_u32_e32 v10, v11, v10
	ds_bpermute_b32 v11, v12, v10
	v_add_u32_e32 v12, -8, v126
	v_cmp_lt_i32_e32 vcc, v12, v8
	s_waitcnt lgkmcnt(0)
	v_cndmask_b32_e64 v11, v11, 0, s[12:13]
	v_cndmask_b32_e32 v12, v12, v126, vcc
	v_lshlrev_b32_e32 v12, 2, v12
	v_add_u32_e32 v10, v11, v10
	ds_bpermute_b32 v11, v12, v10
	v_add_u32_e32 v12, -16, v126
	v_cmp_lt_i32_e32 vcc, v12, v8
	s_waitcnt lgkmcnt(0)
	v_cndmask_b32_e64 v11, v11, 0, s[6:7]
	v_cndmask_b32_e32 v12, v12, v126, vcc
	v_lshlrev_b32_e32 v12, 2, v12
	v_add_u32_e32 v10, v11, v10
	ds_bpermute_b32 v11, v12, v10
	v_subrev_u32_e32 v12, 32, v126
	v_cmp_lt_i32_e32 vcc, v12, v8
	s_waitcnt lgkmcnt(0)
	v_cndmask_b32_e64 v11, v11, 0, s[14:15]
	v_cndmask_b32_e32 v8, v12, v126, vcc
	v_lshlrev_b32_e32 v8, 2, v8
	v_add_u32_e32 v10, v11, v10
	ds_bpermute_b32 v8, v8, v10
	s_waitcnt lgkmcnt(0)
	v_cndmask_b32_e64 v8, v8, 0, s[0:1]
	v_add_u32_e32 v8, v8, v10
	v_lshlrev_b32_e32 v10, 1, v198
	ds_write_b32 v114, v8 offset:33284
	s_and_saveexec_b64 s[46:47], s[10:11]
	s_xor_b64 s[46:47], exec, s[46:47]
	s_cbranch_execz .LBB0_869
	global_store_short v10, v8, s[18:19] offset:2
